# first K-loop body of every unit peeled with C=0 on each accumulator's first MFMA; the 127 v_mov accumulator zeroing per unit removed (P2, P5, P9)
# speedup vs baseline: 1.0080x; 1.0015x over previous
.LBB0_169:
	s_ashr_i32 s15, s14, 31
	s_lshl_b64 s[18:19], s[14:15], 19
	s_add_u32 s18, s89, s18
	s_addc_u32 s19, s90, s19
	s_and_b64 s[56:57], s[0:1], exec
	s_cselect_b32 s15, s19, s65
	s_cselect_b32 s78, s18, s64
	s_ashr_i32 s13, s12, 31
	s_lshl_b64 s[56:57], s[12:13], 19
	s_add_u32 s56, s20, s56
	s_addc_u32 s57, s21, s57
	s_and_b64 s[70:71], s[0:1], exec
	s_cselect_b32 s13, s57, s67
	s_cselect_b32 s79, s56, s66
	s_add_u32 s64, s64, 0x40080
	s_addc_u32 s65, s65, 0
	s_add_u32 s80, s66, 0x100
	v_mov_b32_e32 v2, 0
	s_addc_u32 s81, s67, 0
	s_mov_b32 s82, -2
	ds_read_b128 v[148:151], v144
	ds_read_b128 v[152:155], v144 offset:1024
	ds_read_b128 v[156:159], v144 offset:2048
	ds_read_b128 v[160:163], v144 offset:3072
	ds_read_b128 v[166:169], v145
	ds_read_b128 v[170:173], v145 offset:1024
	ds_read_b128 v[174:177], v145 offset:2048
	ds_read_b128 v[178:181], v145 offset:3072
	s_add_u32 s66, s64, 0xfffc0080
	s_addc_u32 s67, s65, -1
	s_cmp_eq_u32 s82, 12
	s_cselect_b32 s71, s15, s67
	s_cselect_b32 s70, s78, s66
	s_cselect_b32 s67, s13, s81
	s_cselect_b32 s66, s79, s80
	v_lshl_add_u64 v[214:215], s[64:65], 0, v[134:135]
	s_add_i32 m0, s25, 0xc000
	ds_read_b128 v[182:185], v146
	ds_read_b128 v[186:189], v146 offset:1024
	ds_read_b128 v[190:193], v146 offset:2048
	ds_read_b128 v[194:197], v146 offset:3072
	ds_read_b128 v[198:201], v146 offset:4096
	ds_read_b128 v[202:205], v146 offset:5120
	ds_read_b128 v[206:209], v146 offset:6144
	ds_read_b128 v[210:213], v146 offset:7168
	global_load_lds_dwordx4 v[214:215], off
	v_lshl_add_u64 v[214:215], s[64:65], 0, v[136:137]
	s_add_i32 m0, s25, 0xe000
	s_nop 0
	global_load_lds_dwordx4 v[214:215], off
	s_waitcnt vmcnt(8)
	s_waitcnt lgkmcnt(0)
	s_barrier
	s_setprio 1
	s_waitcnt lgkmcnt(0)
	v_mfma_f32_16x16x32_bf16 v[126:129], v[148:151], v[182:185], 0
	v_mfma_f32_16x16x32_bf16 v[118:121], v[156:159], v[182:185], 0
	v_mfma_f32_16x16x32_bf16 v[110:113], v[148:151], v[190:193], 0
	v_mfma_f32_16x16x32_bf16 v[102:105], v[156:159], v[190:193], 0
	v_mfma_f32_16x16x32_bf16 v[94:97], v[148:151], v[198:201], 0
	v_mfma_f32_16x16x32_bf16 v[86:89], v[156:159], v[198:201], 0
	v_mfma_f32_16x16x32_bf16 v[78:81], v[148:151], v[206:209], 0
	v_mfma_f32_16x16x32_bf16 v[70:73], v[156:159], v[206:209], 0
	v_mfma_f32_16x16x32_bf16 v[126:129], v[152:155], v[186:189], v[126:129]
	v_mfma_f32_16x16x32_bf16 v[118:121], v[160:163], v[186:189], v[118:121]
	v_mfma_f32_16x16x32_bf16 v[110:113], v[152:155], v[194:197], v[110:113]
	v_mfma_f32_16x16x32_bf16 v[102:105], v[160:163], v[194:197], v[102:105]
	v_mfma_f32_16x16x32_bf16 v[94:97], v[152:155], v[202:205], v[94:97]
	v_mfma_f32_16x16x32_bf16 v[86:89], v[160:163], v[202:205], v[86:89]
	v_mfma_f32_16x16x32_bf16 v[78:81], v[152:155], v[210:213], v[78:81]
	v_mfma_f32_16x16x32_bf16 v[70:73], v[160:163], v[210:213], v[70:73]
	s_setprio 0
	s_setprio 1
	v_mfma_f32_16x16x32_bf16 v[122:125], v[166:169], v[182:185], 0
	v_mfma_f32_16x16x32_bf16 v[114:117], v[174:177], v[182:185], 0
	v_mfma_f32_16x16x32_bf16 v[106:109], v[166:169], v[190:193], 0
	v_mfma_f32_16x16x32_bf16 v[98:101], v[174:177], v[190:193], 0
	v_mfma_f32_16x16x32_bf16 v[90:93], v[166:169], v[198:201], 0
	v_mfma_f32_16x16x32_bf16 v[82:85], v[174:177], v[198:201], 0
	v_mfma_f32_16x16x32_bf16 v[74:77], v[166:169], v[206:209], 0
	v_mfma_f32_16x16x32_bf16 v[66:69], v[174:177], v[206:209], 0
	v_mfma_f32_16x16x32_bf16 v[122:125], v[170:173], v[186:189], v[122:125]
	v_mfma_f32_16x16x32_bf16 v[114:117], v[178:181], v[186:189], v[114:117]
	v_mfma_f32_16x16x32_bf16 v[106:109], v[170:173], v[194:197], v[106:109]
	v_mfma_f32_16x16x32_bf16 v[98:101], v[178:181], v[194:197], v[98:101]
	v_mfma_f32_16x16x32_bf16 v[90:93], v[170:173], v[202:205], v[90:93]
	v_mfma_f32_16x16x32_bf16 v[82:85], v[178:181], v[202:205], v[82:85]
	v_mfma_f32_16x16x32_bf16 v[74:77], v[170:173], v[210:213], v[74:77]
	v_mfma_f32_16x16x32_bf16 v[66:69], v[178:181], v[210:213], v[66:69]
	s_setprio 0
	s_barrier
	s_add_i32 s83, s74, s22
	v_lshl_add_u64 v[214:215], s[66:67], 0, v[130:131]
	s_mov_b32 m0, s83
	ds_read_b128 v[182:185], v146 offset:16384
	ds_read_b128 v[186:189], v146 offset:17408
	ds_read_b128 v[190:193], v146 offset:18432
	ds_read_b128 v[194:197], v146 offset:19456
	ds_read_b128 v[198:201], v146 offset:20480
	ds_read_b128 v[202:205], v146 offset:21504
	ds_read_b128 v[206:209], v146 offset:22528
	ds_read_b128 v[210:213], v146 offset:23552
	global_load_lds_dwordx4 v[214:215], off
	s_add_i32 m0, s83, 0x2000
	s_add_u32 s84, s66, 0x40000
	v_lshl_add_u64 v[216:217], s[66:67], 0, v[132:133]
	s_addc_u32 s85, s67, 0
	s_add_i32 s83, s75, s22
	global_load_lds_dwordx4 v[216:217], off
	v_lshl_add_u64 v[218:219], s[84:85], 0, v[130:131]
	s_mov_b32 m0, s83
	v_lshl_add_u64 v[220:221], s[70:71], 0, v[132:133]
	global_load_lds_dwordx4 v[218:219], off
	v_lshl_add_u64 v[218:219], s[84:85], 0, v[132:133]
	s_add_i32 m0, s83, 0x2000
	s_nop 0
	global_load_lds_dwordx4 v[218:219], off
	v_lshl_add_u64 v[218:219], s[70:71], 0, v[130:131]
	s_mov_b32 m0, s25
	s_nop 0
	global_load_lds_dwordx4 v[218:219], off
	s_mov_b32 m0, s26
	s_nop 0
	global_load_lds_dwordx4 v[220:221], off
	s_waitcnt vmcnt(8)
	s_waitcnt lgkmcnt(0)
	s_barrier
	s_setprio 1
	s_waitcnt lgkmcnt(0)
	v_mfma_f32_16x16x32_bf16 v[62:65], v[148:151], v[182:185], 0
	v_mfma_f32_16x16x32_bf16 v[54:57], v[156:159], v[182:185], 0
	v_mfma_f32_16x16x32_bf16 v[46:49], v[148:151], v[190:193], 0
	v_mfma_f32_16x16x32_bf16 v[38:41], v[156:159], v[190:193], 0
	v_mfma_f32_16x16x32_bf16 v[30:33], v[148:151], v[198:201], 0
	v_mfma_f32_16x16x32_bf16 v[22:25], v[156:159], v[198:201], 0
	v_mfma_f32_16x16x32_bf16 v[14:17], v[148:151], v[206:209], 0
	v_mfma_f32_16x16x32_bf16 v[6:9], v[156:159], v[206:209], 0
	v_mfma_f32_16x16x32_bf16 v[62:65], v[152:155], v[186:189], v[62:65]
	v_mfma_f32_16x16x32_bf16 v[54:57], v[160:163], v[186:189], v[54:57]
	v_mfma_f32_16x16x32_bf16 v[46:49], v[152:155], v[194:197], v[46:49]
	v_mfma_f32_16x16x32_bf16 v[38:41], v[160:163], v[194:197], v[38:41]
	v_mfma_f32_16x16x32_bf16 v[30:33], v[152:155], v[202:205], v[30:33]
	v_mfma_f32_16x16x32_bf16 v[22:25], v[160:163], v[202:205], v[22:25]
	v_mfma_f32_16x16x32_bf16 v[14:17], v[152:155], v[210:213], v[14:17]
	v_mfma_f32_16x16x32_bf16 v[6:9], v[160:163], v[210:213], v[6:9]
	s_setprio 0
	s_setprio 1
	v_mfma_f32_16x16x32_bf16 v[58:61], v[166:169], v[182:185], 0
	v_mfma_f32_16x16x32_bf16 v[50:53], v[174:177], v[182:185], 0
	v_mfma_f32_16x16x32_bf16 v[42:45], v[166:169], v[190:193], 0
	v_mfma_f32_16x16x32_bf16 v[34:37], v[174:177], v[190:193], 0
	v_mfma_f32_16x16x32_bf16 v[26:29], v[166:169], v[198:201], 0
	v_mfma_f32_16x16x32_bf16 v[18:21], v[174:177], v[198:201], 0
	v_mfma_f32_16x16x32_bf16 v[10:13], v[166:169], v[206:209], 0
	v_mfma_f32_16x16x32_bf16 v[2:5], v[174:177], v[206:209], 0
	v_mfma_f32_16x16x32_bf16 v[58:61], v[170:173], v[186:189], v[58:61]
	v_mfma_f32_16x16x32_bf16 v[50:53], v[178:181], v[186:189], v[50:53]
	v_mfma_f32_16x16x32_bf16 v[42:45], v[170:173], v[194:197], v[42:45]
	v_mfma_f32_16x16x32_bf16 v[34:37], v[178:181], v[194:197], v[34:37]
	v_mfma_f32_16x16x32_bf16 v[26:29], v[170:173], v[202:205], v[26:29]
	v_mfma_f32_16x16x32_bf16 v[18:21], v[178:181], v[202:205], v[18:21]
	v_mfma_f32_16x16x32_bf16 v[10:13], v[170:173], v[210:213], v[10:13]
	v_mfma_f32_16x16x32_bf16 v[2:5], v[178:181], v[210:213], v[2:5]
	s_setprio 0
	s_barrier
	s_add_i32 s83, 0, 0x18000
	v_add_u32_e32 v147, s83, v142
	s_add_i32 s84, 0, 0x1c000
	ds_read_b128 v[148:151], v147
	ds_read_b128 v[152:155], v147 offset:1024
	ds_read_b128 v[156:159], v147 offset:2048
	ds_read_b128 v[160:163], v147 offset:3072
	v_add_u32_e32 v147, s84, v142
	ds_read_b128 v[166:169], v147
	ds_read_b128 v[170:173], v147 offset:1024
	ds_read_b128 v[174:177], v147 offset:2048
	ds_read_b128 v[178:181], v147 offset:3072
	s_add_u32 s70, s70, 0x40000
	s_addc_u32 s71, s71, 0
	s_mov_b32 m0, s27
	v_lshl_add_u64 v[222:223], s[70:71], 0, v[130:131]
	ds_read_b128 v[182:185], v146 offset:32768
	ds_read_b128 v[186:189], v146 offset:33792
	ds_read_b128 v[190:193], v146 offset:34816
	ds_read_b128 v[194:197], v146 offset:35840
	ds_read_b128 v[198:201], v146 offset:36864
	ds_read_b128 v[202:205], v146 offset:37888
	ds_read_b128 v[206:209], v146 offset:38912
	ds_read_b128 v[210:213], v146 offset:39936
	global_load_lds_dwordx4 v[222:223], off
	v_lshl_add_u64 v[222:223], s[70:71], 0, v[132:133]
	s_mov_b32 m0, s63
	s_nop 0
	global_load_lds_dwordx4 v[222:223], off
	s_waitcnt vmcnt(8)
	s_waitcnt lgkmcnt(0)
	s_barrier
	s_setprio 1
	s_waitcnt lgkmcnt(0)
	v_mfma_f32_16x16x32_bf16 v[126:129], v[148:151], v[182:185], v[126:129]
	v_mfma_f32_16x16x32_bf16 v[118:121], v[156:159], v[182:185], v[118:121]
	v_mfma_f32_16x16x32_bf16 v[110:113], v[148:151], v[190:193], v[110:113]
	v_mfma_f32_16x16x32_bf16 v[102:105], v[156:159], v[190:193], v[102:105]
	v_mfma_f32_16x16x32_bf16 v[94:97], v[148:151], v[198:201], v[94:97]
	v_mfma_f32_16x16x32_bf16 v[86:89], v[156:159], v[198:201], v[86:89]
	v_mfma_f32_16x16x32_bf16 v[78:81], v[148:151], v[206:209], v[78:81]
	v_mfma_f32_16x16x32_bf16 v[70:73], v[156:159], v[206:209], v[70:73]
	v_mfma_f32_16x16x32_bf16 v[126:129], v[152:155], v[186:189], v[126:129]
	v_mfma_f32_16x16x32_bf16 v[118:121], v[160:163], v[186:189], v[118:121]
	v_mfma_f32_16x16x32_bf16 v[110:113], v[152:155], v[194:197], v[110:113]
	v_mfma_f32_16x16x32_bf16 v[102:105], v[160:163], v[194:197], v[102:105]
	v_mfma_f32_16x16x32_bf16 v[94:97], v[152:155], v[202:205], v[94:97]
	v_mfma_f32_16x16x32_bf16 v[86:89], v[160:163], v[202:205], v[86:89]
	v_mfma_f32_16x16x32_bf16 v[78:81], v[152:155], v[210:213], v[78:81]
	v_mfma_f32_16x16x32_bf16 v[70:73], v[160:163], v[210:213], v[70:73]
	s_setprio 0
	s_setprio 1
	v_mfma_f32_16x16x32_bf16 v[122:125], v[166:169], v[182:185], v[122:125]
	v_mfma_f32_16x16x32_bf16 v[114:117], v[174:177], v[182:185], v[114:117]
	v_mfma_f32_16x16x32_bf16 v[106:109], v[166:169], v[190:193], v[106:109]
	v_mfma_f32_16x16x32_bf16 v[98:101], v[174:177], v[190:193], v[98:101]
	v_mfma_f32_16x16x32_bf16 v[90:93], v[166:169], v[198:201], v[90:93]
	v_mfma_f32_16x16x32_bf16 v[82:85], v[174:177], v[198:201], v[82:85]
	v_mfma_f32_16x16x32_bf16 v[74:77], v[166:169], v[206:209], v[74:77]
	v_mfma_f32_16x16x32_bf16 v[66:69], v[174:177], v[206:209], v[66:69]
	v_mfma_f32_16x16x32_bf16 v[122:125], v[170:173], v[186:189], v[122:125]
	v_mfma_f32_16x16x32_bf16 v[114:117], v[178:181], v[186:189], v[114:117]
	v_mfma_f32_16x16x32_bf16 v[106:109], v[170:173], v[194:197], v[106:109]
	v_mfma_f32_16x16x32_bf16 v[98:101], v[178:181], v[194:197], v[98:101]
	v_mfma_f32_16x16x32_bf16 v[90:93], v[170:173], v[202:205], v[90:93]
	v_mfma_f32_16x16x32_bf16 v[82:85], v[178:181], v[202:205], v[82:85]
	v_mfma_f32_16x16x32_bf16 v[74:77], v[170:173], v[210:213], v[74:77]
	v_mfma_f32_16x16x32_bf16 v[66:69], v[178:181], v[210:213], v[66:69]
	s_setprio 0
	s_barrier
	s_add_i32 s70, s83, s22
	v_lshl_add_u64 v[214:215], v[214:215], 0, s[8:9]
	s_mov_b32 m0, s70
	ds_read_b128 v[182:185], v146 offset:49152
	ds_read_b128 v[186:189], v146 offset:50176
	ds_read_b128 v[190:193], v146 offset:51200
	ds_read_b128 v[194:197], v146 offset:52224
	ds_read_b128 v[198:201], v146 offset:53248
	ds_read_b128 v[202:205], v146 offset:54272
	ds_read_b128 v[206:209], v146 offset:55296
	ds_read_b128 v[210:213], v146 offset:56320
	global_load_lds_dwordx4 v[214:215], off
	s_add_i32 m0, s70, 0x2000
	s_add_u32 s66, s66, 0x40080
	v_lshl_add_u64 v[214:215], v[216:217], 0, s[8:9]
	s_addc_u32 s67, s67, 0
	s_add_i32 s70, s84, s22
	global_load_lds_dwordx4 v[214:215], off
	v_lshl_add_u64 v[214:215], s[66:67], 0, v[130:131]
	s_mov_b32 m0, s70
	s_nop 0
	global_load_lds_dwordx4 v[214:215], off
	v_lshl_add_u64 v[214:215], s[66:67], 0, v[132:133]
	s_add_i32 m0, s70, 0x2000
	s_nop 0
	global_load_lds_dwordx4 v[214:215], off
	v_lshl_add_u64 v[214:215], v[218:219], 0, s[8:9]
	s_mov_b32 m0, s72
	s_nop 0
	global_load_lds_dwordx4 v[214:215], off
	v_lshl_add_u64 v[214:215], v[220:221], 0, s[8:9]
	s_mov_b32 m0, s73
	s_nop 0
	global_load_lds_dwordx4 v[214:215], off
	s_waitcnt vmcnt(8)
	s_waitcnt lgkmcnt(0)
	s_barrier
	s_setprio 1
	s_waitcnt lgkmcnt(0)
	v_mfma_f32_16x16x32_bf16 v[62:65], v[148:151], v[182:185], v[62:65]
	v_mfma_f32_16x16x32_bf16 v[54:57], v[156:159], v[182:185], v[54:57]
	v_mfma_f32_16x16x32_bf16 v[46:49], v[148:151], v[190:193], v[46:49]
	v_mfma_f32_16x16x32_bf16 v[38:41], v[156:159], v[190:193], v[38:41]
	v_mfma_f32_16x16x32_bf16 v[30:33], v[148:151], v[198:201], v[30:33]
	v_mfma_f32_16x16x32_bf16 v[22:25], v[156:159], v[198:201], v[22:25]
	v_mfma_f32_16x16x32_bf16 v[14:17], v[148:151], v[206:209], v[14:17]
	v_mfma_f32_16x16x32_bf16 v[6:9], v[156:159], v[206:209], v[6:9]
	v_mfma_f32_16x16x32_bf16 v[62:65], v[152:155], v[186:189], v[62:65]
	v_mfma_f32_16x16x32_bf16 v[54:57], v[160:163], v[186:189], v[54:57]
	v_mfma_f32_16x16x32_bf16 v[46:49], v[152:155], v[194:197], v[46:49]
	v_mfma_f32_16x16x32_bf16 v[38:41], v[160:163], v[194:197], v[38:41]
	v_mfma_f32_16x16x32_bf16 v[30:33], v[152:155], v[202:205], v[30:33]
	v_mfma_f32_16x16x32_bf16 v[22:25], v[160:163], v[202:205], v[22:25]
	v_mfma_f32_16x16x32_bf16 v[14:17], v[152:155], v[210:213], v[14:17]
	v_mfma_f32_16x16x32_bf16 v[6:9], v[160:163], v[210:213], v[6:9]
	s_setprio 0
	s_setprio 1
	v_mfma_f32_16x16x32_bf16 v[58:61], v[166:169], v[182:185], v[58:61]
	v_mfma_f32_16x16x32_bf16 v[50:53], v[174:177], v[182:185], v[50:53]
	v_mfma_f32_16x16x32_bf16 v[42:45], v[166:169], v[190:193], v[42:45]
	v_mfma_f32_16x16x32_bf16 v[34:37], v[174:177], v[190:193], v[34:37]
	v_mfma_f32_16x16x32_bf16 v[26:29], v[166:169], v[198:201], v[26:29]
	v_mfma_f32_16x16x32_bf16 v[18:21], v[174:177], v[198:201], v[18:21]
	v_mfma_f32_16x16x32_bf16 v[10:13], v[166:169], v[206:209], v[10:13]
	v_mfma_f32_16x16x32_bf16 v[2:5], v[174:177], v[206:209], v[2:5]
	v_mfma_f32_16x16x32_bf16 v[58:61], v[170:173], v[186:189], v[58:61]
	v_mfma_f32_16x16x32_bf16 v[50:53], v[178:181], v[186:189], v[50:53]
	v_mfma_f32_16x16x32_bf16 v[42:45], v[170:173], v[194:197], v[42:45]
	v_mfma_f32_16x16x32_bf16 v[34:37], v[178:181], v[194:197], v[34:37]
	v_mfma_f32_16x16x32_bf16 v[26:29], v[170:173], v[202:205], v[26:29]
	v_mfma_f32_16x16x32_bf16 v[18:21], v[178:181], v[202:205], v[18:21]
	v_mfma_f32_16x16x32_bf16 v[10:13], v[170:173], v[210:213], v[10:13]
	v_mfma_f32_16x16x32_bf16 v[2:5], v[178:181], v[210:213], v[2:5]
	s_setprio 0
	s_barrier
	s_add_i32 s82, s82, 2
	s_add_u32 s64, s64, 0x100
	s_addc_u32 s65, s65, 0
	s_add_u32 s80, s80, 0x100
	s_addc_u32 s81, s81, 0
	s_cmp_gt_u32 s82, 13
	s_cbranch_scc1 .Lz2_done

.Lz2_done:
	s_and_b64 vcc, exec, s[10:11]
	s_cbranch_vccz .LBB0_173
	s_barrier

.LBB0_459:
	s_ashr_i32 s71, s70, 31
	s_lshl_b64 s[14:15], s[70:71], 19
	s_add_u32 s72, s89, s14
	s_addc_u32 s73, s90, s15
	s_and_b64 s[14:15], s[4:5], exec
	s_cselect_b32 s9, s73, s7
	s_cselect_b32 s11, s72, s6
	s_ashr_i32 s67, s66, 31
	s_lshl_b64 s[14:15], s[66:67], 19
	s_add_u32 s74, s65, s14
	s_addc_u32 s75, s82, s15
	s_and_b64 s[14:15], s[4:5], exec
	s_cselect_b32 s24, s75, s13
	s_cselect_b32 s27, s74, s12
	s_add_u32 s6, s6, 0x40080
	s_addc_u32 s7, s7, 0
	s_add_u32 s67, s12, 0x100
	v_mov_b32_e32 v2, 0
	s_addc_u32 s71, s13, 0
	s_mov_b32 s76, -2
	ds_read_b128 v[130:133], v180
	ds_read_b128 v[134:137], v180 offset:1024
	ds_read_b128 v[158:161], v180 offset:2048
	ds_read_b128 v[184:187], v180 offset:3072
	ds_read_b128 v[188:191], v181
	ds_read_b128 v[192:195], v181 offset:1024
	ds_read_b128 v[196:199], v181 offset:2048
	ds_read_b128 v[200:203], v181 offset:3072
	s_add_u32 s12, s6, 0xfffc0080
	s_addc_u32 s13, s7, -1
	s_cmp_eq_u32 s76, 12
	s_cselect_b32 s15, s9, s13
	s_cselect_b32 s14, s11, s12
	s_cselect_b32 s13, s24, s71
	s_cselect_b32 s12, s27, s67
	v_lshl_add_u64 v[162:163], s[6:7], 0, v[150:151]
	s_add_i32 m0, s84, 0xc000
	ds_read_b128 v[204:207], v182
	ds_read_b128 v[208:211], v182 offset:1024
	ds_read_b128 v[212:215], v182 offset:2048
	ds_read_b128 v[216:219], v182 offset:3072
	ds_read_b128 v[220:223], v182 offset:4096
	ds_read_b128 v[224:227], v182 offset:5120
	ds_read_b128 v[228:231], v182 offset:6144
	ds_read_b128 v[232:235], v182 offset:7168
	global_load_lds_dwordx4 v[162:163], off
	v_lshl_add_u64 v[162:163], s[6:7], 0, v[152:153]
	s_add_i32 m0, s84, 0xe000
	s_nop 0
	global_load_lds_dwordx4 v[162:163], off
	s_waitcnt vmcnt(8)
	s_waitcnt lgkmcnt(0)
	s_barrier
	s_setprio 1
	s_waitcnt lgkmcnt(0)
	v_mfma_f32_16x16x32_bf16 v[126:129], v[130:133], v[204:207], 0
	v_mfma_f32_16x16x32_bf16 v[122:125], v[158:161], v[204:207], 0
	v_mfma_f32_16x16x32_bf16 v[110:113], v[130:133], v[212:215], 0
	v_mfma_f32_16x16x32_bf16 v[106:109], v[158:161], v[212:215], 0
	v_mfma_f32_16x16x32_bf16 v[94:97], v[130:133], v[220:223], 0
	v_mfma_f32_16x16x32_bf16 v[90:93], v[158:161], v[220:223], 0
	v_mfma_f32_16x16x32_bf16 v[78:81], v[130:133], v[228:231], 0
	v_mfma_f32_16x16x32_bf16 v[74:77], v[158:161], v[228:231], 0
	v_mfma_f32_16x16x32_bf16 v[126:129], v[134:137], v[208:211], v[126:129]
	v_mfma_f32_16x16x32_bf16 v[122:125], v[184:187], v[208:211], v[122:125]
	v_mfma_f32_16x16x32_bf16 v[110:113], v[134:137], v[216:219], v[110:113]
	v_mfma_f32_16x16x32_bf16 v[106:109], v[184:187], v[216:219], v[106:109]
	v_mfma_f32_16x16x32_bf16 v[94:97], v[134:137], v[224:227], v[94:97]
	v_mfma_f32_16x16x32_bf16 v[90:93], v[184:187], v[224:227], v[90:93]
	v_mfma_f32_16x16x32_bf16 v[78:81], v[134:137], v[232:235], v[78:81]
	v_mfma_f32_16x16x32_bf16 v[74:77], v[184:187], v[232:235], v[74:77]
	s_setprio 0
	s_setprio 1
	v_mfma_f32_16x16x32_bf16 v[118:121], v[188:191], v[204:207], 0
	v_mfma_f32_16x16x32_bf16 v[114:117], v[196:199], v[204:207], 0
	v_mfma_f32_16x16x32_bf16 v[102:105], v[188:191], v[212:215], 0
	v_mfma_f32_16x16x32_bf16 v[98:101], v[196:199], v[212:215], 0
	v_mfma_f32_16x16x32_bf16 v[86:89], v[188:191], v[220:223], 0
	v_mfma_f32_16x16x32_bf16 v[82:85], v[196:199], v[220:223], 0
	v_mfma_f32_16x16x32_bf16 v[70:73], v[188:191], v[228:231], 0
	v_mfma_f32_16x16x32_bf16 v[66:69], v[196:199], v[228:231], 0
	v_mfma_f32_16x16x32_bf16 v[118:121], v[192:195], v[208:211], v[118:121]
	v_mfma_f32_16x16x32_bf16 v[114:117], v[200:203], v[208:211], v[114:117]
	v_mfma_f32_16x16x32_bf16 v[102:105], v[192:195], v[216:219], v[102:105]
	v_mfma_f32_16x16x32_bf16 v[98:101], v[200:203], v[216:219], v[98:101]
	v_mfma_f32_16x16x32_bf16 v[86:89], v[192:195], v[224:227], v[86:89]
	v_mfma_f32_16x16x32_bf16 v[82:85], v[200:203], v[224:227], v[82:85]
	v_mfma_f32_16x16x32_bf16 v[70:73], v[192:195], v[232:235], v[70:73]
	v_mfma_f32_16x16x32_bf16 v[66:69], v[200:203], v[232:235], v[66:69]
	s_setprio 0
	s_barrier
	s_add_i32 s77, s69, s83
	v_lshl_add_u64 v[162:163], s[12:13], 0, v[138:139]
	s_mov_b32 m0, s77
	ds_read_b128 v[204:207], v182 offset:16384
	ds_read_b128 v[208:211], v182 offset:17408
	ds_read_b128 v[212:215], v182 offset:18432
	ds_read_b128 v[216:219], v182 offset:19456
	ds_read_b128 v[220:223], v182 offset:20480
	ds_read_b128 v[224:227], v182 offset:21504
	ds_read_b128 v[228:231], v182 offset:22528
	ds_read_b128 v[232:235], v182 offset:23552
	global_load_lds_dwordx4 v[162:163], off
	s_add_i32 m0, s77, 0x2000
	s_add_u32 s78, s12, 0x40000
	v_lshl_add_u64 v[236:237], s[12:13], 0, v[140:141]
	s_addc_u32 s79, s13, 0
	s_add_i32 s77, s20, s83
	global_load_lds_dwordx4 v[236:237], off
	v_lshl_add_u64 v[238:239], s[78:79], 0, v[138:139]
	s_mov_b32 m0, s77
	v_lshl_add_u64 v[240:241], s[14:15], 0, v[140:141]
	global_load_lds_dwordx4 v[238:239], off
	v_lshl_add_u64 v[238:239], s[78:79], 0, v[140:141]
	s_add_i32 m0, s77, 0x2000
	s_nop 0
	global_load_lds_dwordx4 v[238:239], off
	v_lshl_add_u64 v[238:239], s[14:15], 0, v[138:139]
	s_mov_b32 m0, s84
	s_nop 0
	global_load_lds_dwordx4 v[238:239], off
	s_mov_b32 m0, s85
	s_nop 0
	global_load_lds_dwordx4 v[240:241], off
	s_waitcnt vmcnt(8)
	s_waitcnt lgkmcnt(0)
	s_barrier
	s_setprio 1
	s_waitcnt lgkmcnt(0)
	v_mfma_f32_16x16x32_bf16 v[62:65], v[130:133], v[204:207], 0
	v_mfma_f32_16x16x32_bf16 v[58:61], v[158:161], v[204:207], 0
	v_mfma_f32_16x16x32_bf16 v[46:49], v[130:133], v[212:215], 0
	v_mfma_f32_16x16x32_bf16 v[42:45], v[158:161], v[212:215], 0
	v_mfma_f32_16x16x32_bf16 v[30:33], v[130:133], v[220:223], 0
	v_mfma_f32_16x16x32_bf16 v[26:29], v[158:161], v[220:223], 0
	v_mfma_f32_16x16x32_bf16 v[14:17], v[130:133], v[228:231], 0
	v_mfma_f32_16x16x32_bf16 v[10:13], v[158:161], v[228:231], 0
	v_mfma_f32_16x16x32_bf16 v[62:65], v[134:137], v[208:211], v[62:65]
	v_mfma_f32_16x16x32_bf16 v[58:61], v[184:187], v[208:211], v[58:61]
	v_mfma_f32_16x16x32_bf16 v[46:49], v[134:137], v[216:219], v[46:49]
	v_mfma_f32_16x16x32_bf16 v[42:45], v[184:187], v[216:219], v[42:45]
	v_mfma_f32_16x16x32_bf16 v[30:33], v[134:137], v[224:227], v[30:33]
	v_mfma_f32_16x16x32_bf16 v[26:29], v[184:187], v[224:227], v[26:29]
	v_mfma_f32_16x16x32_bf16 v[14:17], v[134:137], v[232:235], v[14:17]
	v_mfma_f32_16x16x32_bf16 v[10:13], v[184:187], v[232:235], v[10:13]
	s_setprio 0
	s_setprio 1
	v_mfma_f32_16x16x32_bf16 v[54:57], v[188:191], v[204:207], 0
	v_mfma_f32_16x16x32_bf16 v[50:53], v[196:199], v[204:207], 0
	v_mfma_f32_16x16x32_bf16 v[38:41], v[188:191], v[212:215], 0
	v_mfma_f32_16x16x32_bf16 v[34:37], v[196:199], v[212:215], 0
	v_mfma_f32_16x16x32_bf16 v[22:25], v[188:191], v[220:223], 0
	v_mfma_f32_16x16x32_bf16 v[18:21], v[196:199], v[220:223], 0
	v_mfma_f32_16x16x32_bf16 v[6:9], v[188:191], v[228:231], 0
	v_mfma_f32_16x16x32_bf16 v[2:5], v[196:199], v[228:231], 0
	v_mfma_f32_16x16x32_bf16 v[54:57], v[192:195], v[208:211], v[54:57]
	v_mfma_f32_16x16x32_bf16 v[50:53], v[200:203], v[208:211], v[50:53]
	v_mfma_f32_16x16x32_bf16 v[38:41], v[192:195], v[216:219], v[38:41]
	v_mfma_f32_16x16x32_bf16 v[34:37], v[200:203], v[216:219], v[34:37]
	v_mfma_f32_16x16x32_bf16 v[22:25], v[192:195], v[224:227], v[22:25]
	v_mfma_f32_16x16x32_bf16 v[18:21], v[200:203], v[224:227], v[18:21]
	v_mfma_f32_16x16x32_bf16 v[6:9], v[192:195], v[232:235], v[6:9]
	v_mfma_f32_16x16x32_bf16 v[2:5], v[200:203], v[232:235], v[2:5]
	s_setprio 0
	s_barrier
	s_add_i32 s77, 0, 0x18000
	v_add_u32_e32 v142, s77, v168
	s_add_i32 s78, 0, 0x1c000
	ds_read_b128 v[130:133], v142
	ds_read_b128 v[134:137], v142 offset:1024
	ds_read_b128 v[158:161], v142 offset:2048
	ds_read_b128 v[184:187], v142 offset:3072
	v_add_u32_e32 v142, s78, v168
	ds_read_b128 v[188:191], v142
	ds_read_b128 v[192:195], v142 offset:1024
	ds_read_b128 v[196:199], v142 offset:2048
	ds_read_b128 v[200:203], v142 offset:3072
	s_add_u32 s14, s14, 0x40000
	s_addc_u32 s15, s15, 0
	s_mov_b32 m0, s86
	v_lshl_add_u64 v[242:243], s[14:15], 0, v[138:139]
	ds_read_b128 v[204:207], v182 offset:32768
	ds_read_b128 v[208:211], v182 offset:33792
	ds_read_b128 v[212:215], v182 offset:34816
	ds_read_b128 v[216:219], v182 offset:35840
	ds_read_b128 v[220:223], v182 offset:36864
	ds_read_b128 v[224:227], v182 offset:37888
	ds_read_b128 v[228:231], v182 offset:38912
	ds_read_b128 v[232:235], v182 offset:39936
	global_load_lds_dwordx4 v[242:243], off
	v_lshl_add_u64 v[242:243], s[14:15], 0, v[140:141]
	s_mov_b32 m0, s87
	s_nop 0
	global_load_lds_dwordx4 v[242:243], off
	s_waitcnt vmcnt(8)
	s_waitcnt lgkmcnt(0)
	s_barrier
	s_setprio 1
	s_waitcnt lgkmcnt(0)
	v_mfma_f32_16x16x32_bf16 v[126:129], v[130:133], v[204:207], v[126:129]
	v_mfma_f32_16x16x32_bf16 v[122:125], v[158:161], v[204:207], v[122:125]
	v_mfma_f32_16x16x32_bf16 v[110:113], v[130:133], v[212:215], v[110:113]
	v_mfma_f32_16x16x32_bf16 v[106:109], v[158:161], v[212:215], v[106:109]
	v_mfma_f32_16x16x32_bf16 v[94:97], v[130:133], v[220:223], v[94:97]
	v_mfma_f32_16x16x32_bf16 v[90:93], v[158:161], v[220:223], v[90:93]
	v_mfma_f32_16x16x32_bf16 v[78:81], v[130:133], v[228:231], v[78:81]
	v_mfma_f32_16x16x32_bf16 v[74:77], v[158:161], v[228:231], v[74:77]
	v_mfma_f32_16x16x32_bf16 v[126:129], v[134:137], v[208:211], v[126:129]
	v_mfma_f32_16x16x32_bf16 v[122:125], v[184:187], v[208:211], v[122:125]
	v_mfma_f32_16x16x32_bf16 v[110:113], v[134:137], v[216:219], v[110:113]
	v_mfma_f32_16x16x32_bf16 v[106:109], v[184:187], v[216:219], v[106:109]
	v_mfma_f32_16x16x32_bf16 v[94:97], v[134:137], v[224:227], v[94:97]
	v_mfma_f32_16x16x32_bf16 v[90:93], v[184:187], v[224:227], v[90:93]
	v_mfma_f32_16x16x32_bf16 v[78:81], v[134:137], v[232:235], v[78:81]
	v_mfma_f32_16x16x32_bf16 v[74:77], v[184:187], v[232:235], v[74:77]
	s_setprio 0
	s_setprio 1
	v_mfma_f32_16x16x32_bf16 v[118:121], v[188:191], v[204:207], v[118:121]
	v_mfma_f32_16x16x32_bf16 v[114:117], v[196:199], v[204:207], v[114:117]
	v_mfma_f32_16x16x32_bf16 v[102:105], v[188:191], v[212:215], v[102:105]
	v_mfma_f32_16x16x32_bf16 v[98:101], v[196:199], v[212:215], v[98:101]
	v_mfma_f32_16x16x32_bf16 v[86:89], v[188:191], v[220:223], v[86:89]
	v_mfma_f32_16x16x32_bf16 v[82:85], v[196:199], v[220:223], v[82:85]
	v_mfma_f32_16x16x32_bf16 v[70:73], v[188:191], v[228:231], v[70:73]
	v_mfma_f32_16x16x32_bf16 v[66:69], v[196:199], v[228:231], v[66:69]
	v_mfma_f32_16x16x32_bf16 v[118:121], v[192:195], v[208:211], v[118:121]
	v_mfma_f32_16x16x32_bf16 v[114:117], v[200:203], v[208:211], v[114:117]
	v_mfma_f32_16x16x32_bf16 v[102:105], v[192:195], v[216:219], v[102:105]
	v_mfma_f32_16x16x32_bf16 v[98:101], v[200:203], v[216:219], v[98:101]
	v_mfma_f32_16x16x32_bf16 v[86:89], v[192:195], v[224:227], v[86:89]
	v_mfma_f32_16x16x32_bf16 v[82:85], v[200:203], v[224:227], v[82:85]
	v_mfma_f32_16x16x32_bf16 v[70:73], v[192:195], v[232:235], v[70:73]
	v_mfma_f32_16x16x32_bf16 v[66:69], v[200:203], v[232:235], v[66:69]
	s_setprio 0
	s_barrier
	s_add_i32 s14, s77, s83
	v_lshl_add_u64 v[162:163], v[162:163], 0, s[60:61]
	s_mov_b32 m0, s14
	ds_read_b128 v[204:207], v182 offset:49152
	ds_read_b128 v[208:211], v182 offset:50176
	ds_read_b128 v[212:215], v182 offset:51200
	ds_read_b128 v[216:219], v182 offset:52224
	ds_read_b128 v[220:223], v182 offset:53248
	ds_read_b128 v[224:227], v182 offset:54272
	ds_read_b128 v[228:231], v182 offset:55296
	ds_read_b128 v[232:235], v182 offset:56320
	global_load_lds_dwordx4 v[162:163], off
	s_add_i32 m0, s14, 0x2000
	s_add_u32 s12, s12, 0x40080
	v_lshl_add_u64 v[162:163], v[236:237], 0, s[60:61]
	s_addc_u32 s13, s13, 0
	s_add_i32 s14, s78, s83
	global_load_lds_dwordx4 v[162:163], off
	v_lshl_add_u64 v[162:163], s[12:13], 0, v[138:139]
	s_mov_b32 m0, s14
	s_nop 0
	global_load_lds_dwordx4 v[162:163], off
	v_lshl_add_u64 v[162:163], s[12:13], 0, v[140:141]
	s_add_i32 m0, s14, 0x2000
	s_nop 0
	global_load_lds_dwordx4 v[162:163], off
	v_lshl_add_u64 v[162:163], v[238:239], 0, s[60:61]
	s_mov_b32 m0, s97
	s_nop 0
	global_load_lds_dwordx4 v[162:163], off
	v_lshl_add_u64 v[162:163], v[240:241], 0, s[60:61]
	s_mov_b32 m0, s68
	s_nop 0
	global_load_lds_dwordx4 v[162:163], off
	s_waitcnt vmcnt(8)
	s_waitcnt lgkmcnt(0)
	s_barrier
	s_setprio 1
	s_waitcnt lgkmcnt(0)
	v_mfma_f32_16x16x32_bf16 v[62:65], v[130:133], v[204:207], v[62:65]
	v_mfma_f32_16x16x32_bf16 v[58:61], v[158:161], v[204:207], v[58:61]
	v_mfma_f32_16x16x32_bf16 v[46:49], v[130:133], v[212:215], v[46:49]
	v_mfma_f32_16x16x32_bf16 v[42:45], v[158:161], v[212:215], v[42:45]
	v_mfma_f32_16x16x32_bf16 v[30:33], v[130:133], v[220:223], v[30:33]
	v_mfma_f32_16x16x32_bf16 v[26:29], v[158:161], v[220:223], v[26:29]
	v_mfma_f32_16x16x32_bf16 v[14:17], v[130:133], v[228:231], v[14:17]
	v_mfma_f32_16x16x32_bf16 v[10:13], v[158:161], v[228:231], v[10:13]
	v_mfma_f32_16x16x32_bf16 v[62:65], v[134:137], v[208:211], v[62:65]
	v_mfma_f32_16x16x32_bf16 v[58:61], v[184:187], v[208:211], v[58:61]
	v_mfma_f32_16x16x32_bf16 v[46:49], v[134:137], v[216:219], v[46:49]
	v_mfma_f32_16x16x32_bf16 v[42:45], v[184:187], v[216:219], v[42:45]
	v_mfma_f32_16x16x32_bf16 v[30:33], v[134:137], v[224:227], v[30:33]
	v_mfma_f32_16x16x32_bf16 v[26:29], v[184:187], v[224:227], v[26:29]
	v_mfma_f32_16x16x32_bf16 v[14:17], v[134:137], v[232:235], v[14:17]
	v_mfma_f32_16x16x32_bf16 v[10:13], v[184:187], v[232:235], v[10:13]
	s_setprio 0
	s_setprio 1
	v_mfma_f32_16x16x32_bf16 v[54:57], v[188:191], v[204:207], v[54:57]
	v_mfma_f32_16x16x32_bf16 v[50:53], v[196:199], v[204:207], v[50:53]
	v_mfma_f32_16x16x32_bf16 v[38:41], v[188:191], v[212:215], v[38:41]
	v_mfma_f32_16x16x32_bf16 v[34:37], v[196:199], v[212:215], v[34:37]
	v_mfma_f32_16x16x32_bf16 v[22:25], v[188:191], v[220:223], v[22:25]
	v_mfma_f32_16x16x32_bf16 v[18:21], v[196:199], v[220:223], v[18:21]
	v_mfma_f32_16x16x32_bf16 v[6:9], v[188:191], v[228:231], v[6:9]
	v_mfma_f32_16x16x32_bf16 v[2:5], v[196:199], v[228:231], v[2:5]
	v_mfma_f32_16x16x32_bf16 v[54:57], v[192:195], v[208:211], v[54:57]
	v_mfma_f32_16x16x32_bf16 v[50:53], v[200:203], v[208:211], v[50:53]
	v_mfma_f32_16x16x32_bf16 v[38:41], v[192:195], v[216:219], v[38:41]
	v_mfma_f32_16x16x32_bf16 v[34:37], v[200:203], v[216:219], v[34:37]
	v_mfma_f32_16x16x32_bf16 v[22:25], v[192:195], v[224:227], v[22:25]
	v_mfma_f32_16x16x32_bf16 v[18:21], v[200:203], v[224:227], v[18:21]
	v_mfma_f32_16x16x32_bf16 v[6:9], v[192:195], v[232:235], v[6:9]
	v_mfma_f32_16x16x32_bf16 v[2:5], v[200:203], v[232:235], v[2:5]
	s_setprio 0
	s_barrier
	s_add_i32 s76, s76, 2
	s_add_u32 s6, s6, 0x100
	s_addc_u32 s7, s7, 0
	s_add_u32 s67, s67, 0x100
	s_addc_u32 s71, s71, 0
	s_cmp_gt_u32 s76, 13
	s_cbranch_scc1 .Lz5_done

.Lz5_done:
	s_and_b64 vcc, exec, s[62:63]
	s_cbranch_vccz .LBB0_463
	s_barrier

.LBB0_976:
	s_ashr_i32 s15, s14, 31
	s_lshl_b64 s[18:19], s[14:15], 19
	s_add_u32 s18, s89, s18
	s_addc_u32 s19, s90, s19
	s_and_b64 s[20:21], s[0:1], exec
	s_cselect_b32 s15, s19, s25
	s_cselect_b32 s60, s18, s24
	s_ashr_i32 s13, s12, 31
	s_lshl_b64 s[20:21], s[12:13], 19
	s_add_u32 s20, s26, s20
	s_addc_u32 s21, s27, s21
	s_and_b64 s[44:45], s[0:1], exec
	s_cselect_b32 s13, s21, s37
	s_cselect_b32 s61, s20, s36
	s_add_u32 s24, s24, 0x40080
	s_addc_u32 s25, s25, 0
	s_add_u32 s62, s36, 0x100
	v_mov_b32_e32 v2, 0
	s_addc_u32 s63, s37, 0
	s_mov_b32 s64, -2
	ds_read_b128 v[148:151], v144
	ds_read_b128 v[152:155], v144 offset:1024
	ds_read_b128 v[156:159], v144 offset:2048
	ds_read_b128 v[160:163], v144 offset:3072
	ds_read_b128 v[166:169], v145
	ds_read_b128 v[170:173], v145 offset:1024
	ds_read_b128 v[174:177], v145 offset:2048
	ds_read_b128 v[178:181], v145 offset:3072
	s_add_u32 s36, s24, 0xfffc0080
	s_addc_u32 s37, s25, -1
	s_cmp_eq_u32 s64, 12
	s_cselect_b32 s45, s15, s37
	s_cselect_b32 s44, s60, s36
	s_cselect_b32 s37, s13, s63
	s_cselect_b32 s36, s61, s62
	v_lshl_add_u64 v[214:215], s[24:25], 0, v[134:135]
	s_add_i32 m0, s23, 0xc000
	ds_read_b128 v[182:185], v146
	ds_read_b128 v[186:189], v146 offset:1024
	ds_read_b128 v[190:193], v146 offset:2048
	ds_read_b128 v[194:197], v146 offset:3072
	ds_read_b128 v[198:201], v146 offset:4096
	ds_read_b128 v[202:205], v146 offset:5120
	ds_read_b128 v[206:209], v146 offset:6144
	ds_read_b128 v[210:213], v146 offset:7168
	global_load_lds_dwordx4 v[214:215], off
	v_lshl_add_u64 v[214:215], s[24:25], 0, v[136:137]
	s_add_i32 m0, s23, 0xe000
	s_nop 0
	global_load_lds_dwordx4 v[214:215], off
	s_waitcnt vmcnt(8)
	s_waitcnt lgkmcnt(0)
	s_barrier
	s_setprio 1
	s_waitcnt lgkmcnt(0)
	v_mfma_f32_16x16x32_bf16 v[126:129], v[148:151], v[182:185], 0
	v_mfma_f32_16x16x32_bf16 v[118:121], v[156:159], v[182:185], 0
	v_mfma_f32_16x16x32_bf16 v[110:113], v[148:151], v[190:193], 0
	v_mfma_f32_16x16x32_bf16 v[102:105], v[156:159], v[190:193], 0
	v_mfma_f32_16x16x32_bf16 v[94:97], v[148:151], v[198:201], 0
	v_mfma_f32_16x16x32_bf16 v[86:89], v[156:159], v[198:201], 0
	v_mfma_f32_16x16x32_bf16 v[78:81], v[148:151], v[206:209], 0
	v_mfma_f32_16x16x32_bf16 v[70:73], v[156:159], v[206:209], 0
	v_mfma_f32_16x16x32_bf16 v[126:129], v[152:155], v[186:189], v[126:129]
	v_mfma_f32_16x16x32_bf16 v[118:121], v[160:163], v[186:189], v[118:121]
	v_mfma_f32_16x16x32_bf16 v[110:113], v[152:155], v[194:197], v[110:113]
	v_mfma_f32_16x16x32_bf16 v[102:105], v[160:163], v[194:197], v[102:105]
	v_mfma_f32_16x16x32_bf16 v[94:97], v[152:155], v[202:205], v[94:97]
	v_mfma_f32_16x16x32_bf16 v[86:89], v[160:163], v[202:205], v[86:89]
	v_mfma_f32_16x16x32_bf16 v[78:81], v[152:155], v[210:213], v[78:81]
	v_mfma_f32_16x16x32_bf16 v[70:73], v[160:163], v[210:213], v[70:73]
	s_setprio 0
	s_setprio 1
	v_mfma_f32_16x16x32_bf16 v[122:125], v[166:169], v[182:185], 0
	v_mfma_f32_16x16x32_bf16 v[114:117], v[174:177], v[182:185], 0
	v_mfma_f32_16x16x32_bf16 v[106:109], v[166:169], v[190:193], 0
	v_mfma_f32_16x16x32_bf16 v[98:101], v[174:177], v[190:193], 0
	v_mfma_f32_16x16x32_bf16 v[90:93], v[166:169], v[198:201], 0
	v_mfma_f32_16x16x32_bf16 v[82:85], v[174:177], v[198:201], 0
	v_mfma_f32_16x16x32_bf16 v[74:77], v[166:169], v[206:209], 0
	v_mfma_f32_16x16x32_bf16 v[66:69], v[174:177], v[206:209], 0
	v_mfma_f32_16x16x32_bf16 v[122:125], v[170:173], v[186:189], v[122:125]
	v_mfma_f32_16x16x32_bf16 v[114:117], v[178:181], v[186:189], v[114:117]
	v_mfma_f32_16x16x32_bf16 v[106:109], v[170:173], v[194:197], v[106:109]
	v_mfma_f32_16x16x32_bf16 v[98:101], v[178:181], v[194:197], v[98:101]
	v_mfma_f32_16x16x32_bf16 v[90:93], v[170:173], v[202:205], v[90:93]
	v_mfma_f32_16x16x32_bf16 v[82:85], v[178:181], v[202:205], v[82:85]
	v_mfma_f32_16x16x32_bf16 v[74:77], v[170:173], v[210:213], v[74:77]
	v_mfma_f32_16x16x32_bf16 v[66:69], v[178:181], v[210:213], v[66:69]
	s_setprio 0
	s_barrier
	s_add_i32 s65, s56, s46
	v_lshl_add_u64 v[214:215], s[36:37], 0, v[130:131]
	s_mov_b32 m0, s65
	ds_read_b128 v[182:185], v146 offset:16384
	ds_read_b128 v[186:189], v146 offset:17408
	ds_read_b128 v[190:193], v146 offset:18432
	ds_read_b128 v[194:197], v146 offset:19456
	ds_read_b128 v[198:201], v146 offset:20480
	ds_read_b128 v[202:205], v146 offset:21504
	ds_read_b128 v[206:209], v146 offset:22528
	ds_read_b128 v[210:213], v146 offset:23552
	global_load_lds_dwordx4 v[214:215], off
	s_add_i32 m0, s65, 0x2000
	s_add_u32 s66, s36, 0x40000
	v_lshl_add_u64 v[216:217], s[36:37], 0, v[132:133]
	s_addc_u32 s67, s37, 0
	s_add_i32 s65, s57, s46
	global_load_lds_dwordx4 v[216:217], off
	v_lshl_add_u64 v[218:219], s[66:67], 0, v[130:131]
	s_mov_b32 m0, s65
	v_lshl_add_u64 v[220:221], s[44:45], 0, v[132:133]
	global_load_lds_dwordx4 v[218:219], off
	v_lshl_add_u64 v[218:219], s[66:67], 0, v[132:133]
	s_add_i32 m0, s65, 0x2000
	s_nop 0
	global_load_lds_dwordx4 v[218:219], off
	v_lshl_add_u64 v[218:219], s[44:45], 0, v[130:131]
	s_mov_b32 m0, s23
	s_nop 0
	global_load_lds_dwordx4 v[218:219], off
	s_mov_b32 m0, s49
	s_nop 0
	global_load_lds_dwordx4 v[220:221], off
	s_waitcnt vmcnt(8)
	s_waitcnt lgkmcnt(0)
	s_barrier
	s_setprio 1
	s_waitcnt lgkmcnt(0)
	v_mfma_f32_16x16x32_bf16 v[62:65], v[148:151], v[182:185], 0
	v_mfma_f32_16x16x32_bf16 v[54:57], v[156:159], v[182:185], 0
	v_mfma_f32_16x16x32_bf16 v[46:49], v[148:151], v[190:193], 0
	v_mfma_f32_16x16x32_bf16 v[38:41], v[156:159], v[190:193], 0
	v_mfma_f32_16x16x32_bf16 v[30:33], v[148:151], v[198:201], 0
	v_mfma_f32_16x16x32_bf16 v[22:25], v[156:159], v[198:201], 0
	v_mfma_f32_16x16x32_bf16 v[14:17], v[148:151], v[206:209], 0
	v_mfma_f32_16x16x32_bf16 v[6:9], v[156:159], v[206:209], 0
	v_mfma_f32_16x16x32_bf16 v[62:65], v[152:155], v[186:189], v[62:65]
	v_mfma_f32_16x16x32_bf16 v[54:57], v[160:163], v[186:189], v[54:57]
	v_mfma_f32_16x16x32_bf16 v[46:49], v[152:155], v[194:197], v[46:49]
	v_mfma_f32_16x16x32_bf16 v[38:41], v[160:163], v[194:197], v[38:41]
	v_mfma_f32_16x16x32_bf16 v[30:33], v[152:155], v[202:205], v[30:33]
	v_mfma_f32_16x16x32_bf16 v[22:25], v[160:163], v[202:205], v[22:25]
	v_mfma_f32_16x16x32_bf16 v[14:17], v[152:155], v[210:213], v[14:17]
	v_mfma_f32_16x16x32_bf16 v[6:9], v[160:163], v[210:213], v[6:9]
	s_setprio 0
	s_setprio 1
	v_mfma_f32_16x16x32_bf16 v[58:61], v[166:169], v[182:185], 0
	v_mfma_f32_16x16x32_bf16 v[50:53], v[174:177], v[182:185], 0
	v_mfma_f32_16x16x32_bf16 v[42:45], v[166:169], v[190:193], 0
	v_mfma_f32_16x16x32_bf16 v[34:37], v[174:177], v[190:193], 0
	v_mfma_f32_16x16x32_bf16 v[26:29], v[166:169], v[198:201], 0
	v_mfma_f32_16x16x32_bf16 v[18:21], v[174:177], v[198:201], 0
	v_mfma_f32_16x16x32_bf16 v[10:13], v[166:169], v[206:209], 0
	v_mfma_f32_16x16x32_bf16 v[2:5], v[174:177], v[206:209], 0
	v_mfma_f32_16x16x32_bf16 v[58:61], v[170:173], v[186:189], v[58:61]
	v_mfma_f32_16x16x32_bf16 v[50:53], v[178:181], v[186:189], v[50:53]
	v_mfma_f32_16x16x32_bf16 v[42:45], v[170:173], v[194:197], v[42:45]
	v_mfma_f32_16x16x32_bf16 v[34:37], v[178:181], v[194:197], v[34:37]
	v_mfma_f32_16x16x32_bf16 v[26:29], v[170:173], v[202:205], v[26:29]
	v_mfma_f32_16x16x32_bf16 v[18:21], v[178:181], v[202:205], v[18:21]
	v_mfma_f32_16x16x32_bf16 v[10:13], v[170:173], v[210:213], v[10:13]
	v_mfma_f32_16x16x32_bf16 v[2:5], v[178:181], v[210:213], v[2:5]
	s_setprio 0
	s_barrier
	s_add_i32 s65, 0, 0x18000
	v_add_u32_e32 v147, s65, v142
	s_add_i32 s66, 0, 0x1c000
	ds_read_b128 v[148:151], v147
	ds_read_b128 v[152:155], v147 offset:1024
	ds_read_b128 v[156:159], v147 offset:2048
	ds_read_b128 v[160:163], v147 offset:3072
	v_add_u32_e32 v147, s66, v142
	ds_read_b128 v[166:169], v147
	ds_read_b128 v[170:173], v147 offset:1024
	ds_read_b128 v[174:177], v147 offset:2048
	ds_read_b128 v[178:181], v147 offset:3072
	s_add_u32 s44, s44, 0x40000
	s_addc_u32 s45, s45, 0
	s_mov_b32 m0, s50
	v_lshl_add_u64 v[222:223], s[44:45], 0, v[130:131]
	ds_read_b128 v[182:185], v146 offset:32768
	ds_read_b128 v[186:189], v146 offset:33792
	ds_read_b128 v[190:193], v146 offset:34816
	ds_read_b128 v[194:197], v146 offset:35840
	ds_read_b128 v[198:201], v146 offset:36864
	ds_read_b128 v[202:205], v146 offset:37888
	ds_read_b128 v[206:209], v146 offset:38912
	ds_read_b128 v[210:213], v146 offset:39936
	global_load_lds_dwordx4 v[222:223], off
	v_lshl_add_u64 v[222:223], s[44:45], 0, v[132:133]
	s_mov_b32 m0, s51
	s_nop 0
	global_load_lds_dwordx4 v[222:223], off
	s_waitcnt vmcnt(8)
	s_waitcnt lgkmcnt(0)
	s_barrier
	s_setprio 1
	s_waitcnt lgkmcnt(0)
	v_mfma_f32_16x16x32_bf16 v[126:129], v[148:151], v[182:185], v[126:129]
	v_mfma_f32_16x16x32_bf16 v[118:121], v[156:159], v[182:185], v[118:121]
	v_mfma_f32_16x16x32_bf16 v[110:113], v[148:151], v[190:193], v[110:113]
	v_mfma_f32_16x16x32_bf16 v[102:105], v[156:159], v[190:193], v[102:105]
	v_mfma_f32_16x16x32_bf16 v[94:97], v[148:151], v[198:201], v[94:97]
	v_mfma_f32_16x16x32_bf16 v[86:89], v[156:159], v[198:201], v[86:89]
	v_mfma_f32_16x16x32_bf16 v[78:81], v[148:151], v[206:209], v[78:81]
	v_mfma_f32_16x16x32_bf16 v[70:73], v[156:159], v[206:209], v[70:73]
	v_mfma_f32_16x16x32_bf16 v[126:129], v[152:155], v[186:189], v[126:129]
	v_mfma_f32_16x16x32_bf16 v[118:121], v[160:163], v[186:189], v[118:121]
	v_mfma_f32_16x16x32_bf16 v[110:113], v[152:155], v[194:197], v[110:113]
	v_mfma_f32_16x16x32_bf16 v[102:105], v[160:163], v[194:197], v[102:105]
	v_mfma_f32_16x16x32_bf16 v[94:97], v[152:155], v[202:205], v[94:97]
	v_mfma_f32_16x16x32_bf16 v[86:89], v[160:163], v[202:205], v[86:89]
	v_mfma_f32_16x16x32_bf16 v[78:81], v[152:155], v[210:213], v[78:81]
	v_mfma_f32_16x16x32_bf16 v[70:73], v[160:163], v[210:213], v[70:73]
	s_setprio 0
	s_setprio 1
	v_mfma_f32_16x16x32_bf16 v[122:125], v[166:169], v[182:185], v[122:125]
	v_mfma_f32_16x16x32_bf16 v[114:117], v[174:177], v[182:185], v[114:117]
	v_mfma_f32_16x16x32_bf16 v[106:109], v[166:169], v[190:193], v[106:109]
	v_mfma_f32_16x16x32_bf16 v[98:101], v[174:177], v[190:193], v[98:101]
	v_mfma_f32_16x16x32_bf16 v[90:93], v[166:169], v[198:201], v[90:93]
	v_mfma_f32_16x16x32_bf16 v[82:85], v[174:177], v[198:201], v[82:85]
	v_mfma_f32_16x16x32_bf16 v[74:77], v[166:169], v[206:209], v[74:77]
	v_mfma_f32_16x16x32_bf16 v[66:69], v[174:177], v[206:209], v[66:69]
	v_mfma_f32_16x16x32_bf16 v[122:125], v[170:173], v[186:189], v[122:125]
	v_mfma_f32_16x16x32_bf16 v[114:117], v[178:181], v[186:189], v[114:117]
	v_mfma_f32_16x16x32_bf16 v[106:109], v[170:173], v[194:197], v[106:109]
	v_mfma_f32_16x16x32_bf16 v[98:101], v[178:181], v[194:197], v[98:101]
	v_mfma_f32_16x16x32_bf16 v[90:93], v[170:173], v[202:205], v[90:93]
	v_mfma_f32_16x16x32_bf16 v[82:85], v[178:181], v[202:205], v[82:85]
	v_mfma_f32_16x16x32_bf16 v[74:77], v[170:173], v[210:213], v[74:77]
	v_mfma_f32_16x16x32_bf16 v[66:69], v[178:181], v[210:213], v[66:69]
	s_setprio 0
	s_barrier
	s_add_i32 s44, s65, s46
	v_lshl_add_u64 v[214:215], v[214:215], 0, s[8:9]
	s_mov_b32 m0, s44
	ds_read_b128 v[182:185], v146 offset:49152
	ds_read_b128 v[186:189], v146 offset:50176
	ds_read_b128 v[190:193], v146 offset:51200
	ds_read_b128 v[194:197], v146 offset:52224
	ds_read_b128 v[198:201], v146 offset:53248
	ds_read_b128 v[202:205], v146 offset:54272
	ds_read_b128 v[206:209], v146 offset:55296
	ds_read_b128 v[210:213], v146 offset:56320
	global_load_lds_dwordx4 v[214:215], off
	s_add_i32 m0, s44, 0x2000
	s_add_u32 s36, s36, 0x40080
	v_lshl_add_u64 v[214:215], v[216:217], 0, s[8:9]
	s_addc_u32 s37, s37, 0
	s_add_i32 s44, s66, s46
	global_load_lds_dwordx4 v[214:215], off
	v_lshl_add_u64 v[214:215], s[36:37], 0, v[130:131]
	s_mov_b32 m0, s44
	s_nop 0
	global_load_lds_dwordx4 v[214:215], off
	v_lshl_add_u64 v[214:215], s[36:37], 0, v[132:133]
	s_add_i32 m0, s44, 0x2000
	s_nop 0
	global_load_lds_dwordx4 v[214:215], off
	v_lshl_add_u64 v[214:215], v[218:219], 0, s[8:9]
	s_mov_b32 m0, s54
	s_nop 0
	global_load_lds_dwordx4 v[214:215], off
	v_lshl_add_u64 v[214:215], v[220:221], 0, s[8:9]
	s_mov_b32 m0, s55
	s_nop 0
	global_load_lds_dwordx4 v[214:215], off
	s_waitcnt vmcnt(8)
	s_waitcnt lgkmcnt(0)
	s_barrier
	s_setprio 1
	s_waitcnt lgkmcnt(0)
	v_mfma_f32_16x16x32_bf16 v[62:65], v[148:151], v[182:185], v[62:65]
	v_mfma_f32_16x16x32_bf16 v[54:57], v[156:159], v[182:185], v[54:57]
	v_mfma_f32_16x16x32_bf16 v[46:49], v[148:151], v[190:193], v[46:49]
	v_mfma_f32_16x16x32_bf16 v[38:41], v[156:159], v[190:193], v[38:41]
	v_mfma_f32_16x16x32_bf16 v[30:33], v[148:151], v[198:201], v[30:33]
	v_mfma_f32_16x16x32_bf16 v[22:25], v[156:159], v[198:201], v[22:25]
	v_mfma_f32_16x16x32_bf16 v[14:17], v[148:151], v[206:209], v[14:17]
	v_mfma_f32_16x16x32_bf16 v[6:9], v[156:159], v[206:209], v[6:9]
	v_mfma_f32_16x16x32_bf16 v[62:65], v[152:155], v[186:189], v[62:65]
	v_mfma_f32_16x16x32_bf16 v[54:57], v[160:163], v[186:189], v[54:57]
	v_mfma_f32_16x16x32_bf16 v[46:49], v[152:155], v[194:197], v[46:49]
	v_mfma_f32_16x16x32_bf16 v[38:41], v[160:163], v[194:197], v[38:41]
	v_mfma_f32_16x16x32_bf16 v[30:33], v[152:155], v[202:205], v[30:33]
	v_mfma_f32_16x16x32_bf16 v[22:25], v[160:163], v[202:205], v[22:25]
	v_mfma_f32_16x16x32_bf16 v[14:17], v[152:155], v[210:213], v[14:17]
	v_mfma_f32_16x16x32_bf16 v[6:9], v[160:163], v[210:213], v[6:9]
	s_setprio 0
	s_setprio 1
	v_mfma_f32_16x16x32_bf16 v[58:61], v[166:169], v[182:185], v[58:61]
	v_mfma_f32_16x16x32_bf16 v[50:53], v[174:177], v[182:185], v[50:53]
	v_mfma_f32_16x16x32_bf16 v[42:45], v[166:169], v[190:193], v[42:45]
	v_mfma_f32_16x16x32_bf16 v[34:37], v[174:177], v[190:193], v[34:37]
	v_mfma_f32_16x16x32_bf16 v[26:29], v[166:169], v[198:201], v[26:29]
	v_mfma_f32_16x16x32_bf16 v[18:21], v[174:177], v[198:201], v[18:21]
	v_mfma_f32_16x16x32_bf16 v[10:13], v[166:169], v[206:209], v[10:13]
	v_mfma_f32_16x16x32_bf16 v[2:5], v[174:177], v[206:209], v[2:5]
	v_mfma_f32_16x16x32_bf16 v[58:61], v[170:173], v[186:189], v[58:61]
	v_mfma_f32_16x16x32_bf16 v[50:53], v[178:181], v[186:189], v[50:53]
	v_mfma_f32_16x16x32_bf16 v[42:45], v[170:173], v[194:197], v[42:45]
	v_mfma_f32_16x16x32_bf16 v[34:37], v[178:181], v[194:197], v[34:37]
	v_mfma_f32_16x16x32_bf16 v[26:29], v[170:173], v[202:205], v[26:29]
	v_mfma_f32_16x16x32_bf16 v[18:21], v[178:181], v[202:205], v[18:21]
	v_mfma_f32_16x16x32_bf16 v[10:13], v[170:173], v[210:213], v[10:13]
	v_mfma_f32_16x16x32_bf16 v[2:5], v[178:181], v[210:213], v[2:5]
	s_setprio 0
	s_barrier
	s_add_i32 s64, s64, 2
	s_add_u32 s24, s24, 0x100
	s_addc_u32 s25, s25, 0
	s_add_u32 s62, s62, 0x100
	s_addc_u32 s63, s63, 0
	s_cmp_gt_u32 s64, 13
	s_cbranch_scc1 .Lz9_done
